# address arithmetic: two loop-invariant LDS address adds hoisted out of the sparse-attention compressed pass-B loop
# baseline (speedup 1.0000x reference)
; #define MFMA(a, b, c) __builtin_amdgcn_mfma_f32_32x32x16_bf16((a), (b), (c), 0, 0, 0)
; DI int crow(int i, int h) { return (i & 3) + 8 * (i >> 2) + 4 * h; }
; DI void qk_tile(const bf16_t* sK, const bf16x8 (&qf)[4], f32x16 (&Sx)[2], int r, int h) {
; #pragma unroll
;   for (int mt = 0; mt < 2; ++mt) {
;     f32x16 a;
; #pragma unroll
;     for (int i = 0; i < 16; ++i) a[i] = 0.f;
; #pragma unroll
;     for (int s = 0; s < 4; ++s) {
;       const bf16x8 k = *(const bf16x8*)(sK + (mt * 32 + r) * 72 + s * 16 + h * 8);
;       a = MFMA(k, qf[s], a);
;     }
;     Sx[mt] = a;
;   }
; }
; DI void nsa_item(const Params& p_, const EvenBufs& eb_, int b, int g, int tt, unsigned char* smem) {
;     ...
;   for (int kt = 0; kt < nct; ++kt) {
;     TR_<2> kr; tload(kr, Kc + kt * 64 * 64, 64, tid);
;     __syncthreads();
;     tstore72(kr, sK, tid);
;     __syncthreads();
;     f32x16 Sx[2]; qk_tile(sK, qf, Sx, r, h);
;     unsigned vb = 0;
; #pragma unroll
;     for (int mt = 0; mt < 2; ++mt)
; #pragma unroll
;       for (int i = 0; i < 16; ++i) vb |= (unsigned)(kt * 64 + mt * 32 + crow(i, h) <= nlim) << (mt * 16 + i);
;     online_softmax_t<true>(Sx, vb, m, l);
;   }
.LBB0_1063:
	global_load_dwordx4 v[0:3], v[36:37], off offset:-4096
	global_load_dwordx4 v[4:7], v[36:37], off
	v_add_u32_e32 v16, s66, v167
	v_cmp_le_i32_e32 vcc, v16, v70
	v_cmp_lt_i32_e64 s[6:7], v16, v70
	v_add_u32_e32 v22, 10, v16
	v_cndmask_b32_e64 v17, 0, 1, vcc
	v_cndmask_b32_e64 v18, 0, 2, s[6:7]
	v_add_u32_e32 v23, 11, v16
	v_or_b32_e32 v17, v18, v17
	v_add_u32_e32 v18, 2, v16
	v_add_u32_e32 v19, 3, v16
	v_cmp_gt_i32_e64 s[4:5], v22, v70
	v_cmp_gt_i32_e64 s[12:13], v23, v70
	v_cmp_gt_i32_e64 s[0:1], v18, v70
	v_cmp_gt_i32_e64 s[8:9], v19, v70
	v_add_u32_e32 v20, 8, v16
	v_add_u32_e32 v21, 9, v16
	v_cndmask_b32_e64 v22, 64, 0, s[4:5]
	v_cndmask_b32_e64 v23, v215, 0, s[12:13]
	v_cndmask_b32_e64 v18, 4, 0, s[0:1]
	v_cndmask_b32_e64 v19, 8, 0, s[8:9]
	v_cmp_gt_i32_e64 s[2:3], v20, v70
	v_cmp_gt_i32_e64 s[10:11], v21, v70
	v_or3_b32 v17, v17, v22, v23
	v_cndmask_b32_e64 v20, 16, 0, s[2:3]
	v_cndmask_b32_e64 v21, 32, 0, s[10:11]
	v_or3_b32 v17, v18, v19, v17
	v_or3_b32 v56, v20, v21, v17
	v_add_u32_e32 v17, 16, v16
	v_cmp_gt_i32_e64 s[14:15], v17, v70
	v_add_u32_e32 v18, 17, v16
	s_waitcnt lgkmcnt(0)
	v_cndmask_b32_e64 v17, v216, 0, s[14:15]
	v_cmp_gt_i32_e64 s[14:15], v18, v70
	s_barrier
	s_nop 0
	v_cndmask_b32_e64 v18, v217, 0, s[14:15]
	v_or_b32_e32 v57, v17, v18
	v_add_u32_e32 v17, 18, v16
	v_cmp_gt_i32_e64 s[14:15], v17, v70
	v_add_u32_e32 v18, 19, v16
	s_waitcnt vmcnt(1)
	ds_write_b128 v178, v[0:3]
	s_waitcnt vmcnt(0)
	ds_write_b128 v178, v[4:7] offset:4608
	v_cndmask_b32_e64 v17, v218, 0, s[14:15]
	v_cmp_gt_i32_e64 s[14:15], v18, v70
	s_waitcnt lgkmcnt(0)
	s_barrier
	v_cndmask_b32_e64 v18, v219, 0, s[14:15]
	v_or_b32_e32 v59, v17, v18
	v_add_u32_e32 v17, 24, v16
	v_cmp_gt_i32_e64 s[14:15], v17, v70
	v_add_u32_e32 v18, 25, v16
	s_nop 0
	v_cndmask_b32_e64 v17, v220, 0, s[14:15]
	v_cmp_gt_i32_e64 s[14:15], v18, v70
	ds_read_b128 v[0:3], v179
	ds_read_b128 v[4:7], v179 offset:32
	ds_read_b128 v[8:11], v179 offset:64
	ds_read_b128 v[12:15], v179 offset:96
	ds_read_b128 v[40:43], v179 offset:4608
	ds_read_b128 v[44:47], v179 offset:4640
	ds_read_b128 v[48:51], v179 offset:4672
	ds_read_b128 v[52:55], v179 offset:4704
	v_cndmask_b32_e64 v18, v221, 0, s[14:15]
	v_or_b32_e32 v61, v17, v18
	v_add_u32_e32 v17, 26, v16
	v_cmp_gt_i32_e64 s[14:15], v17, v70
	v_add_u32_e32 v18, 27, v16
	s_movk_i32 s16, 0x200
	v_cndmask_b32_e64 v17, v222, 0, s[14:15]
	v_cmp_gt_i32_e64 s[14:15], v18, v70
	v_or_b32_e32 v58, v57, v56
	v_or_b32_e32 v60, v59, v58
	v_cndmask_b32_e64 v18, v223, 0, s[14:15]
	v_or_b32_e32 v63, v17, v18
	v_add_u32_e32 v17, 32, v16
	v_cmp_gt_i32_e64 s[14:15], v17, v70
	v_add_u32_e32 v18, 33, v16
	v_or_b32_e32 v62, v61, v60
	v_cndmask_b32_e64 v17, v224, 0, s[14:15]
	v_cmp_gt_i32_e64 s[14:15], v18, v70
	v_or_b32_e32 v64, v63, v62
	s_add_i32 s66, s66, 64
	v_cndmask_b32_e64 v18, v225, 0, s[14:15]
	v_or_b32_e32 v65, v17, v18
	v_add_u32_e32 v17, 34, v16
	v_cmp_gt_i32_e64 s[14:15], v17, v70
	v_add_u32_e32 v18, 35, v16
	v_or_b32_e32 v69, v65, v64
	v_cndmask_b32_e64 v17, v226, 0, s[14:15]
	v_cmp_gt_i32_e64 s[14:15], v18, v70
	v_lshl_add_u64 v[36:37], v[36:37], 0, s[76:77]
	s_cmp_eq_u32 s65, s66
	v_cndmask_b32_e64 v18, v227, 0, s[14:15]
	v_or_b32_e32 v72, v17, v18
	v_add_u32_e32 v17, 40, v16
	v_cmp_gt_i32_e64 s[14:15], v17, v70
	v_add_u32_e32 v18, 41, v16
	v_or_b32_e32 v74, v72, v69
	v_cndmask_b32_e64 v17, v228, 0, s[14:15]
	v_cmp_gt_i32_e64 s[14:15], v18, v70
	s_nop 1
	v_cndmask_b32_e64 v18, v229, 0, s[14:15]
	v_or_b32_e32 v75, v17, v18
	v_add_u32_e32 v17, 42, v16
	v_cmp_gt_i32_e64 s[14:15], v17, v70
	v_add_u32_e32 v18, 43, v16
	v_or_b32_e32 v76, v75, v74
	v_cndmask_b32_e64 v17, v230, 0, s[14:15]
	v_cmp_gt_i32_e64 s[14:15], v18, v70
	s_nop 1
	v_cndmask_b32_e64 v18, v231, 0, s[14:15]
	v_or_b32_e32 v77, v17, v18
	v_add_u32_e32 v17, 48, v16
	v_cmp_gt_i32_e64 s[14:15], v17, v70
	v_add_u32_e32 v18, 49, v16
	v_or_b32_e32 v78, v77, v76
	v_cndmask_b32_e64 v17, v232, 0, s[14:15]
	v_cmp_gt_i32_e64 s[14:15], v18, v70
	s_nop 1
	v_cndmask_b32_e64 v18, v233, 0, s[14:15]
	v_or_b32_e32 v79, v17, v18
	v_add_u32_e32 v17, 50, v16
	v_cmp_gt_i32_e64 s[14:15], v17, v70
	v_add_u32_e32 v18, 51, v16
	v_or_b32_e32 v80, v79, v78
	v_cndmask_b32_e64 v17, v234, 0, s[14:15]
	v_cmp_gt_i32_e64 s[14:15], v18, v70
	s_nop 1
	v_cndmask_b32_e64 v18, v235, 0, s[14:15]
	v_or_b32_e32 v81, v17, v18
	v_add_u32_e32 v17, 56, v16
	v_cmp_gt_i32_e64 s[14:15], v17, v70
	v_add_u32_e32 v18, 57, v16
	v_or_b32_e32 v82, v81, v80
	v_cndmask_b32_e64 v17, v236, 0, s[14:15]
	v_cmp_gt_i32_e64 s[14:15], v18, v70
	s_nop 1
	v_cndmask_b32_e64 v18, v237, 0, s[14:15]
	v_or_b32_e32 v83, v17, v18
	v_add_u32_e32 v17, 58, v16
	v_cmp_gt_i32_e64 s[14:15], v17, v70
	v_add_u32_e32 v16, 59, v16
	v_or_b32_e32 v86, v83, v82
	v_cndmask_b32_e64 v17, 2.0, 0, s[14:15]
	v_cmp_gt_i32_e64 s[14:15], v16, v70
	s_nop 1
	v_cndmask_b32_e64 v16, v238, 0, s[14:15]
	v_or_b32_e32 v87, v17, v16
	s_waitcnt lgkmcnt(7)
	v_mfma_f32_32x32x16_bf16 v[16:31], v[0:3], v[138:141], 0
	s_movk_i32 s14, 0x100
	v_or_b32_e32 v88, v87, v86
	v_cmp_lt_i32_e64 s[62:63], -1, v88
	s_waitcnt lgkmcnt(6)
	v_mfma_f32_32x32x16_bf16 v[16:31], v[4:7], v[130:133], v[16:31]
	s_waitcnt lgkmcnt(5)
	v_mfma_f32_32x32x16_bf16 v[16:31], v[8:11], v[134:137], v[16:31]
	s_waitcnt lgkmcnt(4)
	v_mfma_f32_32x32x16_bf16 v[16:31], v[12:15], v[142:145], v[16:31]
	s_waitcnt lgkmcnt(3)
	v_mfma_f32_32x32x16_bf16 v[0:15], v[40:43], v[138:141], 0
	s_nop 9
	v_cndmask_b32_e32 v40, v214, v16, vcc
	v_cndmask_b32_e64 v41, v214, v17, s[6:7]
	v_max3_f32 v16, v40, s92, v41
	v_cndmask_b32_e64 v42, v18, v214, s[0:1]
	v_cndmask_b32_e64 v43, v19, v214, s[8:9]
	v_max3_f32 v16, v16, v42, v43
	v_cndmask_b32_e64 v18, v20, v214, s[2:3]
	s_waitcnt lgkmcnt(2)
; DI float shx32(float v) { return __shfl_xor(v, 32); }
; template <bool MASKED>
; DI float online_softmax_t(f32x16 (&Sx)[2], unsigned vb, float& m, float& l) {
;   float mx = NEG;
; #pragma unroll
;   for (int mt = 0; mt < 2; ++mt)
; #pragma unroll
;     for (int i = 0; i < 16; ++i) {
;       float s = Sx[mt][i];
;       if (MASKED) { s = ((vb >> (mt * 16 + i)) & 1u) ? s : NEG; Sx[mt][i] = s; }
;       mx = fmaxf(mx, s);
;     }
;   mx = fmaxf(mx, shx32(mx));
;   const float mn = fmaxf(m, mx);
;   const float alpha = __builtin_amdgcn_exp2f((m - mn) * L2E);
;   const float mb = mn * L2E;
;   f32x2 sum2 = {0.f, 0.f};
;   const f32x2 l2e2 = {L2E, L2E}, mb2 = {mb, mb};
; #pragma unroll
;   for (int mt = 0; mt < 2; ++mt)
; #pragma unroll
;     for (int i = 0; i < 16; i += 2) {
;       const f32x2 t = (f32x2){Sx[mt][i], Sx[mt][i + 1]} * l2e2 - mb2;
;       f32x2 p = {__builtin_amdgcn_exp2f(t.x), __builtin_amdgcn_exp2f(t.y)};
;       if (MASKED) { p.x = ((vb >> (mt * 16 + i)) & 1u) ? p.x : 0.f; p.y = ((vb >> (mt * 16 + i + 1)) & 1u) ? p.y : 0.f; }
;       Sx[mt][i] = p.x; Sx[mt][i + 1] = p.y;
;       sum2 += p;
;     }
	v_mfma_f32_32x32x16_bf16 v[0:15], v[44:47], v[130:133], v[0:15]
	v_cndmask_b32_e64 v19, v21, v214, s[10:11]
	v_max3_f32 v20, v16, v18, v19
	v_cndmask_b32_e64 v16, v22, v214, s[4:5]
	v_cndmask_b32_e64 v17, v23, v214, s[12:13]
	v_max3_f32 v22, v20, v16, v17
	v_bitop3_b32 v20, v57, s14, v56 bitop3:0xc8
	v_bitop3_b32 v21, v57, s16, v56 bitop3:0xc8
	s_waitcnt lgkmcnt(1)
	v_mfma_f32_32x32x16_bf16 v[0:15], v[48:51], v[134:137], v[0:15]
	v_cmp_eq_u32_e64 s[14:15], 0, v20
	v_cmp_eq_u32_e64 s[18:19], 0, v21
	v_bitop3_b32 v23, v59, s82, v58 bitop3:0xc8
	v_cndmask_b32_e64 v20, v24, v214, s[14:15]
	v_cndmask_b32_e64 v21, v25, v214, s[18:19]
	v_max3_f32 v24, v22, v20, v21
	v_bitop3_b32 v22, v59, s89, v58 bitop3:0xc8
	v_cmp_eq_u32_e64 s[16:17], 0, v22
	v_cmp_eq_u32_e64 s[22:23], 0, v23
	s_waitcnt lgkmcnt(0)
	v_mfma_f32_32x32x16_bf16 v[0:15], v[52:55], v[142:145], v[0:15]
	v_cndmask_b32_e64 v22, v26, v214, s[16:17]
	v_cndmask_b32_e64 v23, v27, v214, s[22:23]
	v_max3_f32 v26, v24, v22, v23
	v_bitop3_b32 v24, v61, s90, v60 bitop3:0xc8
	v_bitop3_b32 v25, v61, s91, v60 bitop3:0xc8
	v_cmp_eq_u32_e64 s[20:21], 0, v24
	v_cmp_eq_u32_e64 s[26:27], 0, v25
	v_bitop3_b32 v27, v63, s70, v62 bitop3:0xc8
	v_cndmask_b32_e64 v24, v28, v214, s[20:21]
	v_cndmask_b32_e64 v25, v29, v214, s[26:27]
	v_max3_f32 v28, v26, v24, v25
	v_bitop3_b32 v26, v63, s94, v62 bitop3:0xc8
	v_cmp_eq_u32_e64 s[24:25], 0, v26
	v_cmp_eq_u32_e64 s[30:31], 0, v27
	v_cndmask_b32_e64 v15, v15, v214, s[62:63]
	v_cndmask_b32_e64 v26, v30, v214, s[24:25]
	v_cndmask_b32_e64 v27, v31, v214, s[30:31]
	v_max3_f32 v30, v28, v26, v27
	v_bitop3_b32 v28, v65, s71, v64 bitop3:0xc8
	v_cmp_eq_u32_e64 s[28:29], 0, v28
	s_nop 1
	v_cndmask_b32_e64 v28, v0, v214, s[28:29]
	v_bitop3_b32 v0, v65, s55, v64 bitop3:0xc8
	v_cmp_eq_u32_e64 s[36:37], 0, v0
	s_nop 1
	v_cndmask_b32_e64 v29, v1, v214, s[36:37]
	v_bitop3_b32 v1, v72, s52, v69 bitop3:0xc8
	v_cmp_eq_u32_e64 s[34:35], 0, v1
	v_bitop3_b32 v1, v72, s50, v69 bitop3:0xc8
	v_cmp_eq_u32_e64 s[40:41], 0, v1
	v_bitop3_b32 v1, v75, s51, v74 bitop3:0xc8
	v_cmp_eq_u32_e64 s[38:39], 0, v1
	v_bitop3_b32 v1, v75, s56, v74 bitop3:0xc8
	v_cmp_eq_u32_e64 s[44:45], 0, v1
	v_bitop3_b32 v1, v77, s57, v76 bitop3:0xc8
	v_cmp_eq_u32_e64 s[42:43], 0, v1
	v_bitop3_b32 v1, v77, s79, v76 bitop3:0xc8
	v_cmp_eq_u32_e64 s[48:49], 0, v1
	v_bitop3_b32 v1, v79, s33, v78 bitop3:0xc8
	v_cmp_eq_u32_e64 s[46:47], 0, v1
	v_bitop3_b32 v1, v79, s68, v78 bitop3:0xc8
	v_max3_f32 v0, v30, v28, v29
	v_cndmask_b32_e64 v2, v2, v214, s[34:35]
	v_cndmask_b32_e64 v3, v3, v214, s[40:41]
	v_cmp_eq_u32_e64 s[52:53], 0, v1
	v_bitop3_b32 v1, v81, s69, v80 bitop3:0xc8
	v_max3_f32 v0, v0, v2, v3
	v_cndmask_b32_e64 v4, v4, v214, s[38:39]
	v_cndmask_b32_e64 v5, v5, v214, s[44:45]
	v_cmp_eq_u32_e64 s[50:51], 0, v1
	v_bitop3_b32 v1, v81, s72, v80 bitop3:0xc8
	v_max3_f32 v0, v0, v4, v5
	v_cndmask_b32_e64 v6, v6, v214, s[42:43]
	v_cndmask_b32_e64 v7, v7, v214, s[48:49]
	v_cmp_eq_u32_e64 s[56:57], 0, v1
	v_bitop3_b32 v1, v83, s73, v82 bitop3:0xc8
	v_max3_f32 v0, v0, v6, v7
	v_cndmask_b32_e64 v8, v8, v214, s[46:47]
	v_cndmask_b32_e64 v9, v9, v214, s[52:53]
	v_cmp_eq_u32_e64 s[54:55], 0, v1
	v_bitop3_b32 v1, v83, s74, v82 bitop3:0xc8
	v_max3_f32 v0, v0, v8, v9
	v_cndmask_b32_e64 v10, v10, v214, s[50:51]
	v_cndmask_b32_e64 v11, v11, v214, s[56:57]
	v_cmp_eq_u32_e64 s[60:61], 0, v1
	v_bitop3_b32 v1, v87, 2.0, v86 bitop3:0xc8
	v_max3_f32 v0, v0, v10, v11
	v_cndmask_b32_e64 v12, v12, v214, s[54:55]
	v_cndmask_b32_e64 v13, v13, v214, s[60:61]
	v_cmp_eq_u32_e64 s[58:59], 0, v1
	v_max3_f32 v0, v0, v12, v13
	s_nop 0
	v_cndmask_b32_e64 v14, v14, v214, s[58:59]
	v_max3_f32 v0, v0, v14, v15
	ds_bpermute_b32 v1, v169, v0
	s_waitcnt lgkmcnt(0)
	v_max3_f32 v0, v35, v0, v1
	v_mul_f32_e32 v72, 0x3fb8aa3b, v0
	v_pk_fma_f32 v[30:31], v[40:41], s[96:97], v[72:73] op_sel_hi:[1,0,0] neg_lo:[0,0,1] neg_hi:[0,0,1]
	v_pk_fma_f32 v[40:41], v[42:43], s[96:97], v[72:73] op_sel_hi:[1,0,0] neg_lo:[0,0,1] neg_hi:[0,0,1]
	v_exp_f32_e32 v1, v30
	v_pk_fma_f32 v[18:19], v[18:19], s[96:97], v[72:73] op_sel_hi:[1,0,0] neg_lo:[0,0,1] neg_hi:[0,0,1]
	v_exp_f32_e32 v31, v31
	v_exp_f32_e32 v41, v41
	v_cndmask_b32_e32 v30, 0, v1, vcc
	v_exp_f32_e32 v1, v40
	v_exp_f32_e32 v19, v19
	v_pk_fma_f32 v[16:17], v[16:17], s[96:97], v[72:73] op_sel_hi:[1,0,0] neg_lo:[0,0,1] neg_hi:[0,0,1]
	v_cndmask_b32_e64 v31, 0, v31, s[6:7]
	v_cndmask_b32_e64 v40, v1, 0, s[0:1]
	v_exp_f32_e32 v1, v18
	v_exp_f32_e32 v17, v17
	v_pk_add_f32 v[30:31], v[30:31], 0 op_sel_hi:[1,0]
	v_cndmask_b32_e64 v41, v41, 0, s[8:9]
	v_cndmask_b32_e64 v18, v1, 0, s[2:3]
	v_exp_f32_e32 v1, v16
	v_pk_add_f32 v[30:31], v[40:41], v[30:31]
	v_cndmask_b32_e64 v19, v19, 0, s[10:11]
	v_pk_add_f32 v[18:19], v[18:19], v[30:31]
	v_cndmask_b32_e64 v16, v1, 0, s[4:5]
	v_cndmask_b32_e64 v17, v17, 0, s[12:13]
	v_pk_add_f32 v[16:17], v[16:17], v[18:19]
	v_pk_fma_f32 v[18:19], v[20:21], s[96:97], v[72:73] op_sel_hi:[1,0,0] neg_lo:[0,0,1] neg_hi:[0,0,1]
	v_pk_fma_f32 v[2:3], v[2:3], s[96:97], v[72:73] op_sel_hi:[1,0,0] neg_lo:[0,0,1] neg_hi:[0,0,1]
	v_exp_f32_e32 v1, v18
	v_exp_f32_e32 v19, v19
	v_exp_f32_e32 v3, v3
	v_pk_fma_f32 v[4:5], v[4:5], s[96:97], v[72:73] op_sel_hi:[1,0,0] neg_lo:[0,0,1] neg_hi:[0,0,1]
	v_cndmask_b32_e64 v18, v1, 0, s[14:15]
	v_cndmask_b32_e64 v19, v19, 0, s[18:19]
	v_pk_add_f32 v[16:17], v[18:19], v[16:17]
	v_pk_fma_f32 v[18:19], v[22:23], s[96:97], v[72:73] op_sel_hi:[1,0,0] neg_lo:[0,0,1] neg_hi:[0,0,1]
	v_exp_f32_e32 v5, v5
	v_exp_f32_e32 v1, v18
	v_exp_f32_e32 v19, v19
	v_cndmask_b32_e64 v3, v3, 0, s[40:41]
	v_cndmask_b32_e64 v5, v5, 0, s[44:45]
	v_cndmask_b32_e64 v18, v1, 0, s[16:17]
; DI float shx32(float v) { return __shfl_xor(v, 32); }
; template <bool MASKED>
; DI float online_softmax_t(f32x16 (&Sx)[2], unsigned vb, float& m, float& l) {
;     ...
;   l = l * alpha + (sum2.x + sum2.y);
;   m = mn;
;   return alpha;
; DI void nsa_item(const Params& p_, const EvenBufs& eb_, int b, int g, int tt, unsigned char* smem) {
;     ...
;   l += shx32(l);
;   const float invl = l > 0.f ? 1.f / l : 0.f;
;   const float mb = m * L2E;
;   zero_o<2>(O);
;   float carry_prev = 0.f;
;   for (int kt = 0; kt < nct; ++kt) {
;     TR_<2> kr, vr; tload(kr, Kc + kt * 64 * 64, 64, tid); tload(vr, VcT + kt * 64, 256, tid);
	v_cndmask_b32_e64 v19, v19, 0, s[22:23]
	v_pk_add_f32 v[16:17], v[18:19], v[16:17]
	v_pk_fma_f32 v[18:19], v[24:25], s[96:97], v[72:73] op_sel_hi:[1,0,0] neg_lo:[0,0,1] neg_hi:[0,0,1]
	s_nop 0
	v_exp_f32_e32 v1, v18
	v_exp_f32_e32 v19, v19
	v_cndmask_b32_e64 v18, v1, 0, s[20:21]
	v_cndmask_b32_e64 v19, v19, 0, s[26:27]
	v_pk_add_f32 v[16:17], v[18:19], v[16:17]
	v_pk_fma_f32 v[18:19], v[26:27], s[96:97], v[72:73] op_sel_hi:[1,0,0] neg_lo:[0,0,1] neg_hi:[0,0,1]
	s_nop 0
	v_exp_f32_e32 v1, v18
	v_exp_f32_e32 v19, v19
	v_cndmask_b32_e64 v18, v1, 0, s[24:25]
	v_cndmask_b32_e64 v19, v19, 0, s[30:31]
	v_pk_add_f32 v[16:17], v[18:19], v[16:17]
	v_pk_fma_f32 v[18:19], v[28:29], s[96:97], v[72:73] op_sel_hi:[1,0,0] neg_lo:[0,0,1] neg_hi:[0,0,1]
	s_nop 0
	v_exp_f32_e32 v1, v18
	v_exp_f32_e32 v19, v19
	v_cndmask_b32_e64 v18, v1, 0, s[28:29]
	v_exp_f32_e32 v1, v2
	v_cndmask_b32_e64 v19, v19, 0, s[36:37]
	v_pk_add_f32 v[16:17], v[18:19], v[16:17]
	v_cndmask_b32_e64 v2, v1, 0, s[34:35]
	v_exp_f32_e32 v1, v4
	v_pk_add_f32 v[2:3], v[2:3], v[16:17]
	v_cndmask_b32_e64 v4, v1, 0, s[38:39]
	v_pk_add_f32 v[2:3], v[4:5], v[2:3]
	v_pk_fma_f32 v[4:5], v[6:7], s[96:97], v[72:73] op_sel_hi:[1,0,0] neg_lo:[0,0,1] neg_hi:[0,0,1]
	s_nop 0
	v_exp_f32_e32 v1, v4
	v_exp_f32_e32 v5, v5
	v_cndmask_b32_e64 v4, v1, 0, s[42:43]
	v_cndmask_b32_e64 v5, v5, 0, s[48:49]
	v_pk_add_f32 v[2:3], v[4:5], v[2:3]
	v_pk_fma_f32 v[4:5], v[8:9], s[96:97], v[72:73] op_sel_hi:[1,0,0] neg_lo:[0,0,1] neg_hi:[0,0,1]
	s_nop 0
	v_exp_f32_e32 v1, v4
	v_exp_f32_e32 v5, v5
	v_cndmask_b32_e64 v4, v1, 0, s[46:47]
	v_cndmask_b32_e64 v5, v5, 0, s[52:53]
	v_pk_add_f32 v[2:3], v[4:5], v[2:3]
	v_pk_fma_f32 v[4:5], v[10:11], s[96:97], v[72:73] op_sel_hi:[1,0,0] neg_lo:[0,0,1] neg_hi:[0,0,1]
	s_mov_b32 s52, 0x40000
	v_exp_f32_e32 v1, v4
	v_exp_f32_e32 v5, v5
	v_cndmask_b32_e64 v4, v1, 0, s[50:51]
	v_cndmask_b32_e64 v5, v5, 0, s[56:57]
	v_pk_add_f32 v[2:3], v[4:5], v[2:3]
	v_pk_fma_f32 v[4:5], v[12:13], s[96:97], v[72:73] op_sel_hi:[1,0,0] neg_lo:[0,0,1] neg_hi:[0,0,1]
	s_mov_b32 s51, 0x100000
	v_exp_f32_e32 v1, v4
	v_exp_f32_e32 v5, v5
	s_mov_b32 s50, 0x80000
	s_mov_b32 s57, 0x400000
	v_cndmask_b32_e64 v4, v1, 0, s[54:55]
	v_cndmask_b32_e64 v5, v5, 0, s[60:61]
	v_pk_add_f32 v[2:3], v[4:5], v[2:3]
	v_pk_fma_f32 v[4:5], v[14:15], s[96:97], v[72:73] op_sel_hi:[1,0,0] neg_lo:[0,0,1] neg_hi:[0,0,1]
	s_mov_b32 s56, 0x200000
	v_exp_f32_e32 v1, v4
	v_exp_f32_e32 v5, v5
	s_mov_b32 s55, 0x20000
	v_cndmask_b32_e64 v4, v1, 0, s[58:59]
	v_sub_f32_e32 v1, v35, v0
	v_mul_f32_e32 v1, 0x3fb8aa3b, v1
	v_cndmask_b32_e64 v5, v5, 0, s[62:63]
	v_exp_f32_e32 v1, v1
	v_pk_add_f32 v[2:3], v[4:5], v[2:3]
	v_mov_b32_e32 v35, v0
	v_add_f32_e32 v2, v2, v3
	v_mov_b32_e32 v3, v39
	v_mov_b32_e32 v39, v2
	v_fmac_f32_e32 v39, v3, v1
	s_cbranch_scc0 .LBB0_1063
	ds_bpermute_b32 v2, v169, v39
	v_readlane_b32 s0, v255, 20
	v_readlane_b32 s1, v255, 21
	s_add_u32 s0, s0, s67
	s_addc_u32 s1, s1, 0
	v_mov_b32_e32 v35, v33
	v_lshl_add_u64 v[0:1], s[0:1], 0, v[34:35]
	s_mov_b64 s[2:3], 0xd516000
	v_lshl_add_u64 v[78:79], v[0:1], 0, s[2:3]
	s_waitcnt lgkmcnt(0)
	v_add_f32_e32 v0, v39, v2
	v_div_scale_f32 v1, s[2:3], v0, v0, 1.0
	v_rcp_f32_e32 v2, v1
	s_add_u32 s0, s0, 0xd55a000
	v_add_u32_e32 v74, 32, v66
	s_movk_i32 s2, 0x88
	v_fma_f32 v3, -v1, v2, 1.0
	v_fmac_f32_e32 v2, v3, v2
	v_div_scale_f32 v3, vcc, 1.0, v0, 1.0
	v_mul_f32_e32 v4, v3, v2
	v_fma_f32 v5, -v1, v4, v3
	v_fmac_f32_e32 v4, v5, v2
	v_fma_f32 v1, -v1, v4, v3
	v_div_fmas_f32 v1, v1, v2, v4
	v_div_fixup_f32 v1, v1, v0, 1.0
	v_cmp_lt_f32_e32 vcc, 0, v0
	v_lshlrev_b32_e32 v3, 13, v85
	v_lshlrev_b32_e32 v4, 8, v71
	v_cndmask_b32_e32 v80, 0, v1, vcc
	v_lshlrev_b64 v[0:1], 9, v[66:67]
	s_addc_u32 s1, s1, 0
	v_ashrrev_i32_e32 v75, 31, v74
	v_mov_b32_e32 v88, 0
	v_mul_lo_u32 v2, v66, s2
	v_sub_u32_e32 v5, v32, v38
	v_mul_u32_u24_e32 v6, 0x88, v71
	v_or3_b32 v3, v3, v4, v167
	v_lshl_add_u64 v[0:1], s[0:1], 0, v[0:1]
	s_mov_b32 s80, 0
	v_lshlrev_b64 v[76:77], 7, v[74:75]
	v_cmp_gt_u32_e32 vcc, 32, v84
	v_mov_b32_e32 v69, v70
	v_mov_b32_e32 v81, v80
	v_add_u32_e32 v32, 0x4800, v3
	v_lshl_add_u64 v[82:83], v[0:1], 0, v[116:117]
	v_add_u32_e32 v86, v34, v2
	v_add_u32_e32 v87, v5, v6
	s_mov_b32 s2, s80
	v_mov_b32_e32 v16, 0
	v_mov_b32_e32 v17, v88
	v_mov_b32_e32 v18, v88
	v_mov_b32_e32 v19, v88
	v_mov_b32_e32 v20, v88
	v_mov_b32_e32 v21, v88
	v_mov_b32_e32 v22, v88
	v_mov_b32_e32 v23, v88
	v_mov_b32_e32 v24, v88
	v_mov_b32_e32 v25, v88
	v_mov_b32_e32 v26, v88
	v_mov_b32_e32 v27, v88
	v_mov_b32_e32 v28, v88
	v_mov_b32_e32 v29, v88
	v_mov_b32_e32 v30, v88
	v_mov_b32_e32 v31, v88
	v_mov_b32_e32 v0, 0
	v_mov_b32_e32 v1, v88
	v_mov_b32_e32 v2, v88
	v_mov_b32_e32 v3, v88
	v_mov_b32_e32 v4, v88
	v_mov_b32_e32 v5, v88
	v_mov_b32_e32 v6, v88
	v_mov_b32_e32 v7, v88
	v_mov_b32_e32 v8, v88
	v_mov_b32_e32 v9, v88
	v_mov_b32_e32 v10, v88
	v_mov_b32_e32 v11, v88
	v_mov_b32_e32 v12, v88
	v_mov_b32_e32 v13, v88
	v_mov_b32_e32 v14, v88
	v_mov_b32_e32 v15, v88
	v_add_u32_e32 v180, 0x2400, v86
	v_add_u32_e32 v181, 0x3500, v86
; DI int crow(int i, int h) { return (i & 3) + 8 * (i >> 2) + 4 * h; }
; DI float shx32(float v) { return __shfl_xor(v, 32); }
; DI void nsa_item(const Params& p_, const EvenBufs& eb_, int b, int g, int tt, unsigned char* smem) {
;     ...
;   for (int kt = 0; kt < nct; ++kt) {
;     TR_<2> kr, vr; tload(kr, Kc + kt * 64 * 64, 64, tid); tload(vr, VcT + kt * 64, 256, tid);
;     __syncthreads();
;     tstore72(kr, sK, tid); tstore68(vr, sV, tid);
;     __syncthreads();
;     f32x16 Sx[2]; qk_tile(sK, qf, Sx, r, h);
; #pragma unroll
;     for (int mt = 0; mt < 2; ++mt) {
; #pragma unroll
;       for (int i = 0; i < 16; ++i) {
;         const bool ok = (kt * 64 + mt * 32 + crow(i, h)) <= nlim;
;         const float pr = __builtin_amdgcn_exp2f(Sx[mt][i] * L2E - mb) * invl;
;         Sx[mt][i] = ok ? pr : 0.f;
;       }
;       float x[4];
; #pragma unroll
;       for (int gg = 0; gg < 4; ++gg) x[gg] = shx32(Sx[mt][4 * gg + 3]);
; #pragma unroll
;       for (int gg = 0; gg < 4; ++gg) {
;         const float prev = h ? x[gg] : (gg ? x[gg > 0 ? gg - 1 : 0] : carry_prev);
;         const float val = Sx[mt][4 * gg] + Sx[mt][4 * gg + 1] + Sx[mt][4 * gg + 2] + Sx[mt][4 * gg + 3] + prev;
;         impW[(wid * 32 + r) * 64 + kt * 16 + mt * 8 + 2 * gg + h] = val;
;       }
;       carry_prev = x[3];
;     }
;     pv_tile<2>(sV, Sx, O, r, h);
;   }
.LBB0_1065:
	v_add_u32_e32 v89, s2, v167
	v_add_u32_e32 v89, 59, v89
	v_cmp_gt_i32_e64 s[98:99], v89, v70
	s_cmp_eq_u64 s[98:99], 0
	s_cbranch_scc1 .Lcmpb_fast
	v_lshl_add_u64 v[38:39], s[80:81], 1, v[78:79]
	v_lshl_add_u64 v[34:35], v[38:39], 0, v[114:115]
	v_lshl_add_u64 v[38:39], v[38:39], 0, v[76:77]
	global_load_dwordx4 v[34:37], v[34:35], off
	s_nop 0
	global_load_dwordx4 v[38:41], v[38:39], off
	s_movk_i32 s0, 0xc000
	v_add_co_u32_e64 v42, s[0:1], s0, v82
	s_nop 1
	v_addc_co_u32_e64 v43, s[0:1], -1, v83, s[0:1]
	global_load_dwordx4 v[42:45], v[42:43], off
	s_nop 0
	global_load_dwordx4 v[46:49], v[82:83], off
	s_barrier
	s_waitcnt vmcnt(3)
	ds_write_b128 v178, v[34:37]
	s_waitcnt vmcnt(2)
	ds_write_b128 v178, v[38:41] offset:4608
	s_waitcnt vmcnt(1)
	ds_write2_b64 v180, v[42:43], v[44:45] offset1:1
	s_waitcnt vmcnt(0)
	ds_write2_b64 v181, v[46:47], v[48:49] offset1:1
	s_waitcnt lgkmcnt(0)
	s_barrier
	ds_read_b128 v[34:37], v179
	ds_read_b128 v[38:41], v179 offset:32
	s_waitcnt lgkmcnt(1)
	v_mfma_f32_32x32x16_bf16 v[50:65], v[34:37], v[138:141], 0
	ds_read_b128 v[34:37], v179 offset:64
	ds_read_b128 v[90:93], v179 offset:4640
	v_add_u32_e32 v89, s2, v167
	v_cmp_le_i32_e64 s[0:1], v89, v70
	v_add_u32_e32 v182, 0x2000, v87
	v_add_u32_e32 v183, 0x3000, v87
	s_addk_i32 s80, 0x1000
	s_waitcnt lgkmcnt(2)
	v_mfma_f32_32x32x16_bf16 v[50:65], v[38:41], v[130:133], v[50:65]
	s_waitcnt lgkmcnt(1)
	v_mfma_f32_32x32x16_bf16 v[50:65], v[34:37], v[134:137], v[50:65]
	ds_read_b128 v[34:37], v179 offset:96
	s_waitcnt lgkmcnt(0)
	v_mfma_f32_32x32x16_bf16 v[50:65], v[34:37], v[142:145], v[50:65]
	ds_read_b128 v[34:37], v179 offset:4608
	s_waitcnt lgkmcnt(0)
	v_mfma_f32_32x32x16_bf16 v[34:49], v[34:37], v[138:141], 0
	s_nop 8
	v_fma_f32 v50, v50, s96, -v72
	v_exp_f32_e32 v50, v50
	s_nop 0
	v_mul_f32_e32 v50, v80, v50
	v_mfma_f32_32x32x16_bf16 v[34:49], v[90:93], v[130:133], v[34:49]
	ds_read_b128 v[90:93], v179 offset:4672
	s_waitcnt lgkmcnt(0)
	v_mfma_f32_32x32x16_bf16 v[34:49], v[90:93], v[134:137], v[34:49]
	ds_read_b128 v[90:93], v179 offset:4704
	s_waitcnt lgkmcnt(0)
	v_mfma_f32_32x32x16_bf16 v[34:49], v[90:93], v[142:145], v[34:49]
	v_cndmask_b32_e64 v91, 0, v50, s[0:1]
	v_fma_f32 v50, v51, s96, -v72
	v_exp_f32_e32 v50, v50
	v_cmp_lt_i32_e64 s[0:1], v89, v70
	v_fma_f32 v51, v53, s96, -v72
	v_exp_f32_e32 v51, v51
	v_mul_f32_e32 v50, v80, v50
	v_cndmask_b32_e64 v92, 0, v50, s[0:1]
	v_fma_f32 v50, v52, s96, -v72
	v_exp_f32_e32 v50, v50
	v_or_b32_e32 v52, 3, v89
	v_or_b32_e32 v53, 2, v89
	v_cmp_le_i32_e64 s[0:1], v52, v69
	v_pk_mul_f32 v[50:51], v[80:81], v[50:51]
	v_or_b32_e32 v52, 9, v89
	v_cndmask_b32_e64 v93, 0, v51, s[0:1]
	v_cmp_le_i32_e64 s[0:1], v53, v70
	v_fma_f32 v51, v55, s96, -v72
	v_exp_f32_e32 v51, v51
	v_cndmask_b32_e64 v94, 0, v50, s[0:1]
	v_fma_f32 v50, v54, s96, -v72
	v_exp_f32_e32 v50, v50
	v_or_b32_e32 v53, 8, v89
	v_cmp_le_i32_e64 s[0:1], v52, v69
	v_or_b32_e32 v52, 11, v89
	v_pk_mul_f32 v[50:51], v[80:81], v[50:51]
	v_or_b32_e32 v54, 17, v89
	v_cndmask_b32_e64 v95, 0, v51, s[0:1]
	v_cmp_le_i32_e64 s[0:1], v53, v70
	v_fma_f32 v51, v57, s96, -v72
	v_exp_f32_e32 v51, v51
	v_cndmask_b32_e64 v96, 0, v50, s[0:1]
	v_fma_f32 v50, v56, s96, -v72
	v_exp_f32_e32 v50, v50
	v_or_b32_e32 v53, 10, v89
	v_cmp_le_i32_e64 s[0:1], v52, v69
	v_or_b32_e32 v55, 16, v89
	v_pk_mul_f32 v[50:51], v[80:81], v[50:51]
	v_or_b32_e32 v56, 19, v89
	v_cndmask_b32_e64 v97, 0, v51, s[0:1]
	v_cmp_le_i32_e64 s[0:1], v53, v70
	v_fma_f32 v51, v59, s96, -v72
	v_exp_f32_e32 v51, v51
	v_cndmask_b32_e64 v98, 0, v50, s[0:1]
	v_fma_f32 v50, v58, s96, -v72
	v_exp_f32_e32 v50, v50
	v_cmp_le_i32_e64 s[0:1], v54, v69
	v_or_b32_e32 v57, 18, v89
	v_or_b32_e32 v58, 25, v89
	v_pk_mul_f32 v[52:53], v[80:81], v[50:51]
	v_or_b32_e32 v59, 24, v89
	v_cndmask_b32_e64 v50, 0, v53, s[0:1]
	v_cmp_le_i32_e64 s[0:1], v55, v70
	v_fma_f32 v53, v61, s96, -v72
	v_exp_f32_e32 v53, v53
	v_cndmask_b32_e64 v51, 0, v52, s[0:1]
	v_fma_f32 v52, v60, s96, -v72
	v_exp_f32_e32 v52, v52
	v_cmp_le_i32_e64 s[0:1], v56, v69
	v_or_b32_e32 v60, 27, v89
	v_or_b32_e32 v61, 26, v89
	v_pk_mul_f32 v[54:55], v[80:81], v[52:53]
	v_add_u32_e32 v90, s2, v32
	v_cndmask_b32_e64 v52, 0, v55, s[0:1]
	v_cmp_le_i32_e64 s[0:1], v57, v70
	v_fma_f32 v55, v63, s96, -v72
	v_exp_f32_e32 v55, v55
	v_cndmask_b32_e64 v53, 0, v54, s[0:1]
	v_fma_f32 v54, v62, s96, -v72
	v_exp_f32_e32 v54, v54
	v_cmp_le_i32_e64 s[0:1], v58, v69
	v_add_f32_e32 v62, v91, v92
	v_add_f32_e32 v62, v94, v62
	v_pk_mul_f32 v[56:57], v[80:81], v[54:55]
	v_add_f32_e32 v62, v93, v62
	v_cndmask_b32_e64 v54, 0, v57, s[0:1]
	v_cmp_le_i32_e64 s[0:1], v59, v70
	v_fma_f32 v57, v65, s96, -v72
	v_exp_f32_e32 v57, v57
	v_cndmask_b32_e64 v55, 0, v56, s[0:1]
	v_fma_f32 v56, v64, s96, -v72
	v_exp_f32_e32 v56, v56
	v_cmp_le_i32_e64 s[0:1], v60, v69
	ds_bpermute_b32 v60, v169, v52
	v_fma_f32 v34, v34, s96, -v72
	v_pk_mul_f32 v[58:59], v[80:81], v[56:57]
	v_fma_f32 v35, v35, s96, -v72
	v_cndmask_b32_e64 v56, 0, v59, s[0:1]
	v_cmp_le_i32_e64 s[0:1], v61, v70
	ds_bpermute_b32 v59, v169, v97
	ds_bpermute_b32 v99, v169, v56
	v_cndmask_b32_e64 v57, 0, v58, s[0:1]
	ds_bpermute_b32 v58, v169, v93
	v_exp_f32_e32 v34, v34
	v_exp_f32_e32 v35, v35
	s_add_i32 s2, s2, 64
	s_cmp_eq_u32 s65, s2
	s_waitcnt lgkmcnt(0)
; DI unsigned pack2(float a, float b) { bf2_t v = __builtin_convertvector((f32x2){a, b}, bf2_t); return __builtin_bit_cast(unsigned, v); }
; #define MFMA(a, b, c) __builtin_amdgcn_mfma_f32_32x32x16_bf16((a), (b), (c), 0, 0, 0)
; DI int crow(int i, int h) { return (i & 3) + 8 * (i >> 2) + 4 * h; }
; DI float shx32(float v) { return __shfl_xor(v, 32); }
; template <int NDT> DI void pv_tile(const bf16_t* sV, const f32x16 (&P)[2], f32x16 (&O)[NDT], int r, int h) {
; #pragma unroll
;   for (int mt = 0; mt < 2; ++mt)
; #pragma unroll
;     for (int sp = 0; sp < 2; ++sp) {
;       u32x4 pk;
;       pk.x = pack2(P[mt][8 * sp + 0], P[mt][8 * sp + 1]); pk.y = pack2(P[mt][8 * sp + 2], P[mt][8 * sp + 3]);
;       pk.z = pack2(P[mt][8 * sp + 4], P[mt][8 * sp + 5]); pk.w = pack2(P[mt][8 * sp + 6], P[mt][8 * sp + 7]);
;       const bf16x8 pb = __builtin_bit_cast(bf16x8, pk);
; #pragma unroll
;       for (int dt = 0; dt < NDT; ++dt) {
;         const bf16_t* vp = sV + (dt * 32 + r) * 68 + mt * 32 + sp * 16 + 4 * h;
;         const bf16x4 lo = *(const bf16x4*)vp, hi = *(const bf16x4*)(vp + 8);
;         const bf16x8 va = __builtin_shufflevector(lo, hi, 0, 1, 2, 3, 4, 5, 6, 7);
;         O[dt] = MFMA(va, pb, O[dt]);
;       }
;       if (NDT > 2) __builtin_amdgcn_sched_barrier(0);
;     }
; }
; DI void nsa_item(const Params& p_, const EvenBufs& eb_, int b, int g, int tt, unsigned char* smem) {
;     ...
;     for (int mt = 0; mt < 2; ++mt) {
; #pragma unroll
;       for (int i = 0; i < 16; ++i) {
;         const bool ok = (kt * 64 + mt * 32 + crow(i, h)) <= nlim;
;         const float pr = __builtin_amdgcn_exp2f(Sx[mt][i] * L2E - mb) * invl;
;         Sx[mt][i] = ok ? pr : 0.f;
;       }
;       float x[4];
; #pragma unroll
;       for (int gg = 0; gg < 4; ++gg) x[gg] = shx32(Sx[mt][4 * gg + 3]);
; #pragma unroll
;       for (int gg = 0; gg < 4; ++gg) {
;         const float prev = h ? x[gg] : (gg ? x[gg > 0 ? gg - 1 : 0] : carry_prev);
;         const float val = Sx[mt][4 * gg] + Sx[mt][4 * gg + 1] + Sx[mt][4 * gg + 2] + Sx[mt][4 * gg + 3] + prev;
;         impW[(wid * 32 + r) * 64 + kt * 16 + mt * 8 + 2 * gg + h] = val;
;       }
;       carry_prev = x[3];
;     }
;     pv_tile<2>(sV, Sx, O, r, h);
;   }
	v_cndmask_b32_e32 v61, v58, v88, vcc
	v_add_f32_e32 v61, v62, v61
	v_add_f32_e32 v62, v96, v95
	v_add_f32_e32 v62, v98, v62
	v_cndmask_b32_e32 v58, v59, v58, vcc
	v_add_f32_e32 v62, v97, v62
	v_add_f32_e32 v58, v62, v58
	ds_write2_b32 v90, v61, v58 offset1:2
	v_cndmask_b32_e32 v58, v60, v59, vcc
	v_add_f32_e32 v59, v51, v50
	v_add_f32_e32 v59, v53, v59
	v_add_f32_e32 v59, v52, v59
	v_add_f32_e32 v58, v59, v58
	v_cndmask_b32_e32 v59, v99, v60, vcc
	v_add_f32_e32 v60, v55, v54
	v_add_f32_e32 v60, v57, v60
	v_add_f32_e32 v60, v56, v60
	v_add_f32_e32 v59, v60, v59
	ds_write2_b32 v90, v58, v59 offset0:4 offset1:6
	v_or_b32_e32 v58, 33, v89
	v_or_b32_e32 v59, 32, v89
	v_pk_mul_f32 v[34:35], v[80:81], v[34:35]
	v_cmp_le_i32_e64 s[0:1], v58, v69
	s_nop 1
	v_cndmask_b32_e64 v58, 0, v35, s[0:1]
	v_cmp_le_i32_e64 s[0:1], v59, v70
	v_fma_f32 v35, v37, s96, -v72
	v_exp_f32_e32 v35, v35
	v_cndmask_b32_e64 v59, 0, v34, s[0:1]
	v_fma_f32 v34, v36, s96, -v72
	v_exp_f32_e32 v34, v34
	v_or_b32_e32 v36, 35, v89
	v_or_b32_e32 v37, 34, v89
	v_cmp_le_i32_e64 s[0:1], v36, v69
	v_pk_mul_f32 v[34:35], v[80:81], v[34:35]
	v_or_b32_e32 v36, 41, v89
	v_cndmask_b32_e64 v60, 0, v35, s[0:1]
	v_cmp_le_i32_e64 s[0:1], v37, v70
	v_fma_f32 v35, v39, s96, -v72
	v_exp_f32_e32 v35, v35
	v_cndmask_b32_e64 v61, 0, v34, s[0:1]
	v_fma_f32 v34, v38, s96, -v72
	v_exp_f32_e32 v34, v34
	v_or_b32_e32 v37, 40, v89
	v_cmp_le_i32_e64 s[0:1], v36, v69
	v_or_b32_e32 v36, 43, v89
	v_pk_mul_f32 v[34:35], v[80:81], v[34:35]
	v_add_f32_e32 v38, v59, v58
	v_cndmask_b32_e64 v62, 0, v35, s[0:1]
	v_cmp_le_i32_e64 s[0:1], v37, v70
	v_fma_f32 v35, v41, s96, -v72
	v_exp_f32_e32 v35, v35
	v_cndmask_b32_e64 v63, 0, v34, s[0:1]
	v_fma_f32 v34, v40, s96, -v72
	v_exp_f32_e32 v34, v34
	v_or_b32_e32 v37, 42, v89
	v_cmp_le_i32_e64 s[0:1], v36, v69
	v_or_b32_e32 v36, 49, v89
	v_pk_mul_f32 v[34:35], v[80:81], v[34:35]
	v_add_f32_e32 v38, v61, v38
	v_cndmask_b32_e64 v64, 0, v35, s[0:1]
	v_cmp_le_i32_e64 s[0:1], v37, v70
	v_fma_f32 v35, v43, s96, -v72
	v_exp_f32_e32 v35, v35
	v_cndmask_b32_e64 v65, 0, v34, s[0:1]
	v_fma_f32 v34, v42, s96, -v72
	v_exp_f32_e32 v34, v34
	v_or_b32_e32 v37, 48, v89
	v_cmp_le_i32_e64 s[0:1], v36, v69
	v_or_b32_e32 v36, 51, v89
	v_pk_mul_f32 v[34:35], v[80:81], v[34:35]
	v_add_f32_e32 v38, v60, v38
	v_cndmask_b32_e64 v42, 0, v35, s[0:1]
	v_cmp_le_i32_e64 s[0:1], v37, v70
	v_fma_f32 v35, v45, s96, -v72
	v_exp_f32_e32 v35, v35
	v_cndmask_b32_e64 v43, 0, v34, s[0:1]
	v_fma_f32 v34, v44, s96, -v72
	v_exp_f32_e32 v34, v34
	v_or_b32_e32 v37, 50, v89
	v_cmp_le_i32_e64 s[0:1], v36, v69
	v_or_b32_e32 v36, 57, v89
	v_pk_mul_f32 v[34:35], v[80:81], v[34:35]
	s_nop 0
	v_cndmask_b32_e64 v44, 0, v35, s[0:1]
	v_cmp_le_i32_e64 s[0:1], v37, v70
	v_fma_f32 v35, v47, s96, -v72
	v_exp_f32_e32 v35, v35
	v_cndmask_b32_e64 v45, 0, v34, s[0:1]
	v_fma_f32 v34, v46, s96, -v72
	v_exp_f32_e32 v34, v34
	v_or_b32_e32 v37, 56, v89
	v_cmp_le_i32_e64 s[0:1], v36, v69
	v_or_b32_e32 v36, 59, v89
	v_pk_mul_f32 v[34:35], v[80:81], v[34:35]
	s_nop 0
	v_cndmask_b32_e64 v46, 0, v35, s[0:1]
	v_cmp_le_i32_e64 s[0:1], v37, v70
	v_fma_f32 v35, v49, s96, -v72
	v_exp_f32_e32 v35, v35
	v_cndmask_b32_e64 v47, 0, v34, s[0:1]
	v_fma_f32 v34, v48, s96, -v72
	v_exp_f32_e32 v34, v34
	v_or_b32_e32 v37, 58, v89
	v_cmp_le_i32_e64 s[0:1], v36, v69
	ds_bpermute_b32 v36, v169, v44
	v_pk_mul_f32 v[34:35], v[80:81], v[34:35]
	s_nop 0
	v_cndmask_b32_e64 v48, 0, v35, s[0:1]
	v_cmp_le_i32_e64 s[0:1], v37, v70
	ds_bpermute_b32 v35, v169, v64
	ds_bpermute_b32 v88, v169, v48
	v_cndmask_b32_e64 v49, 0, v34, s[0:1]
	ds_bpermute_b32 v34, v169, v60
	s_mov_b64 s[0:1], 0x80
	v_lshl_add_u64 v[82:83], v[82:83], 0, s[0:1]
	s_waitcnt lgkmcnt(0)
	v_cndmask_b32_e32 v37, v34, v99, vcc
	v_add_f32_e32 v37, v38, v37
	v_add_f32_e32 v38, v63, v62
	v_add_f32_e32 v38, v65, v38
	v_cndmask_b32_e32 v34, v35, v34, vcc
	v_add_f32_e32 v38, v64, v38
	v_add_f32_e32 v34, v38, v34
	ds_write2_b32 v90, v37, v34 offset0:8 offset1:10
	v_cndmask_b32_e32 v34, v36, v35, vcc
	v_add_f32_e32 v35, v43, v42
	v_add_f32_e32 v35, v45, v35
	v_add_f32_e32 v35, v44, v35
	v_add_f32_e32 v34, v35, v34
	v_cndmask_b32_e32 v35, v88, v36, vcc
	v_add_f32_e32 v36, v47, v46
	v_add_f32_e32 v36, v49, v36
	v_add_f32_e32 v36, v48, v36
	v_add_f32_e32 v35, v36, v35
	ds_write2_b32 v90, v34, v35 offset0:12 offset1:14
	v_cvt_pk_bf16_f32 v34, v91, v92
	v_cvt_pk_bf16_f32 v35, v94, v93
	ds_read2_b64 v[90:93], v182 offset0:128 offset1:130
	ds_read2_b64 v[38:41], v182 offset0:132 offset1:134
	v_cvt_pk_bf16_f32 v36, v96, v95
	v_cvt_pk_bf16_f32 v37, v98, v97
	s_waitcnt lgkmcnt(1)
	s_nop 0
	v_mfma_f32_32x32x16_bf16 v[16:31], v[90:93], v[34:37], v[16:31]
	ds_read2_b64 v[90:93], v183 offset0:160 offset1:162
	s_waitcnt lgkmcnt(0)
	v_mfma_f32_32x32x16_bf16 v[0:15], v[90:93], v[34:37], v[0:15]
	v_cvt_pk_bf16_f32 v34, v51, v50
	v_cvt_pk_bf16_f32 v35, v53, v52
	v_cvt_pk_bf16_f32 v36, v55, v54
	v_cvt_pk_bf16_f32 v37, v57, v56
	s_nop 1
	v_mfma_f32_32x32x16_bf16 v[16:31], v[38:41], v[34:37], v[16:31]
	ds_read2_b64 v[38:41], v183 offset0:164 offset1:166
	s_waitcnt lgkmcnt(0)
	v_mfma_f32_32x32x16_bf16 v[0:15], v[38:41], v[34:37], v[0:15]
	ds_read2_b64 v[38:41], v182 offset0:136 offset1:138
	v_cvt_pk_bf16_f32 v34, v59, v58
	v_cvt_pk_bf16_f32 v35, v61, v60
	v_cvt_pk_bf16_f32 v36, v63, v62
	v_cvt_pk_bf16_f32 v37, v65, v64
	s_waitcnt lgkmcnt(0)
	s_nop 0
	v_mfma_f32_32x32x16_bf16 v[16:31], v[38:41], v[34:37], v[16:31]
	ds_read2_b64 v[38:41], v183 offset0:168 offset1:170
	s_waitcnt lgkmcnt(0)
	v_mfma_f32_32x32x16_bf16 v[0:15], v[38:41], v[34:37], v[0:15]
	ds_read2_b64 v[38:41], v182 offset0:140 offset1:142
	v_cvt_pk_bf16_f32 v34, v43, v42
	v_cvt_pk_bf16_f32 v35, v45, v44
	v_cvt_pk_bf16_f32 v36, v47, v46
	v_cvt_pk_bf16_f32 v37, v49, v48
	s_waitcnt lgkmcnt(0)
	s_nop 0
	v_mfma_f32_32x32x16_bf16 v[16:31], v[38:41], v[34:37], v[16:31]
	ds_read2_b64 v[38:41], v183 offset0:172 offset1:174
	s_waitcnt lgkmcnt(0)
	v_mfma_f32_32x32x16_bf16 v[0:15], v[38:41], v[34:37], v[0:15]
	s_cbranch_scc0 .LBB0_1065
